# v033 + write-through (sc1) for the paired EpiC ACT stores (P9)
# baseline (speedup 1.0000x reference)
; #define LAS __attribute__((address_space(3)))
;     __device__ __forceinline__ void operator()(const f32x4 (&acc)[2][2][4][2], const CU2& u, int wr, int wc, int fr_, int fq_) const {
;     ...
;         for (int n = 0; n < 2; ++n) {
;             const float* wp = cw + 128 * u.pn + cl + 4 * n; const float* bp = cb + 128 * u.pn + cl + 4 * n;
;             const f32x4 g0 = *(const f32x4*)wp, g1 = *(const f32x4*)(wp + 2 * FF_), g2 = *(const f32x4*)(wp + 4 * FF_), gb = *(const f32x4*)bp;
;             const f32x4 v0 = *(const f32x4*)(wp + FF_), v1 = *(const f32x4*)(wp + 3 * FF_), v2 = *(const f32x4*)(wp + 5 * FF_), vb = *(const f32x4*)(bp + FF_);
;             f32x4 pg2 = acc[1][0][2][n] * rsv[6], pg1 = acc[1][0][3][n] * rsv[7], pv2 = acc[1][1][2][n] * rsv[6], pv1 = acc[1][1][3][n] * rsv[7];
; #pragma unroll
;             for (int e = 0; e < 4; ++e) {
;                 pg2[e] = __int_as_float(__builtin_amdgcn_mov_dpp(__float_as_int(pg2[e]), 0x111, 0xF, 0xF, true)); pg1[e] = __int_as_float(__builtin_amdgcn_mov_dpp(__float_as_int(pg1[e]), 0x111, 0xF, 0xF, true));
;                 pv2[e] = __int_as_float(__builtin_amdgcn_mov_dpp(__float_as_int(pv2[e]), 0x111, 0xF, 0xF, true)); pv1[e] = __int_as_float(__builtin_amdgcn_mov_dpp(__float_as_int(pv1[e]), 0x111, 0xF, 0xF, true));
;             }
;             if (fr == 0 && wr == 1) { pg2 = *(const LAS f32x4*)(hal + cl + 4 * n); pg1 = *(const LAS f32x4*)(hal + 256 + cl + 4 * n); pv2 = *(const LAS f32x4*)(hal + 128 + cl + 4 * n); pv1 = *(const LAS f32x4*)(hal + 384 + cl + 4 * n); }
; #pragma unroll
;             for (int j = 0; j < 8; ++j) {
;                 const f32x4 xg = acc[j >> 2][0][j & 3][n] * rsv[j], xv = acc[j >> 2][1][j & 3][n] * rsv[j];
;                 const f32x4 gc = gb + g2 * xg + g1 * pg1 + g0 * pg2, vc = vb + v2 * xv + v1 * pv1 + v0 * pv2;
;                 f32x4 sg;
; #pragma unroll
;                 for (int e = 0; e < 4; ++e) sg[e] = __builtin_amdgcn_rcpf(1.f + __expf(-gc[e]));
;                 const f32x4 o4 = gc * sg * vc;
;                 pg2 = pg1; pg1 = xg; pv2 = pv1; pv1 = xv;
;                 if (rb + j >= 2 && tb + j < T_) { u32x2 w; w.x = cvt_pk_bf16(o4[0], o4[1]); w.y = cvt_pk_bf16(o4[2], o4[3]); *(u32x2*)(act + (size_t)(tb + j) * FF_ + 128 * u.pn + cl + 4 * n) = w; }
.LBB0_949:
	s_or_b64 exec, exec, s[30:31]
	v_mov_b32_e32 v229, v228
	v_mov_b32_e32 v114, v228
	v_mov_b32_e32 v115, v228
	v_pk_mul_f32 v[60:61], v[60:61], v[114:115]
	v_pk_mul_f32 v[58:59], v[58:59], v[228:229]
	v_pk_mul_f32 v[42:43], v[42:43], v[114:115]
	v_pk_mul_f32 v[40:41], v[40:41], v[228:229]
	s_and_saveexec_b64 s[4:5], s[10:11]
	s_cbranch_execz .LBB0_951
	s_waitcnt lgkmcnt(0)
	v_pk_fma_f32 v[114:115], v[42:43], v[102:103], v[106:107]
	v_pk_fma_f32 v[116:117], v[40:41], v[100:101], v[104:105]
	s_waitcnt lgkmcnt(0)
	v_pk_fma_f32 v[114:115], v[98:99], v[56:57], v[114:115]
	v_pk_fma_f32 v[116:117], v[96:97], v[54:55], v[116:117]
	v_pk_fma_f32 v[74:75], v[82:83], v[74:75], v[114:115]
	v_pk_fma_f32 v[72:73], v[80:81], v[72:73], v[116:117]
	v_pk_fma_f32 v[114:115], v[60:61], v[90:91], v[94:95]
	v_pk_fma_f32 v[116:117], v[58:59], v[88:89], v[92:93]
	v_pk_fma_f32 v[114:115], v[86:87], v[46:47], v[114:115]
	v_pk_fma_f32 v[116:117], v[84:85], v[44:45], v[116:117]
	v_pk_fma_f32 v[70:71], v[78:79], v[70:71], v[114:115]
	v_pk_fma_f32 v[68:69], v[76:77], v[68:69], v[116:117]
	v_mul_f32_e32 v116, 0xbfb8aa3b, v70
	v_mul_f32_e32 v114, 0xbfb8aa3b, v68
	v_mul_f32_e32 v115, 0xbfb8aa3b, v69
	v_mul_f32_e32 v117, 0xbfb8aa3b, v71
	v_exp_f32_e32 v114, v114
	v_exp_f32_e32 v115, v115
	v_exp_f32_e32 v116, v116
	v_exp_f32_e32 v117, v117
	v_add_f32_e32 v114, 1.0, v114
	v_add_f32_e32 v115, 1.0, v115
	v_add_f32_e32 v116, 1.0, v116
	v_add_f32_e32 v117, 1.0, v117
	v_rcp_f32_e32 v114, v114
	v_rcp_f32_e32 v115, v115
	v_rcp_f32_e32 v116, v116
	v_rcp_f32_e32 v117, v117
	v_pk_mul_f32 v[68:69], v[68:69], v[114:115]
	s_nop 0
	v_pk_mul_f32 v[68:69], v[72:73], v[68:69]
	v_pk_mul_f32 v[70:71], v[70:71], v[116:117]
	v_cvt_pk_bf16_f32 v150, v68, v69
	s_nop 0
	v_pk_mul_f32 v[70:71], v[74:75], v[70:71]
	s_nop 0
	v_cvt_pk_bf16_f32 v151, v70, v71
	v_mad_i64_i32 v[70:71], s[10:11], v200, s37, v[50:51]
	global_store_dwordx4 v[70:71], v[148:151], off sc1
.LBB0_951:
	s_or_b64 exec, exec, s[4:5]
	v_mov_b32_e32 v225, v224
	s_waitcnt lgkmcnt(0)
	v_mov_b32_e32 v68, v224
	v_mov_b32_e32 v69, v224
	v_pk_mul_f32 v[38:39], v[38:39], v[68:69]
	v_pk_mul_f32 v[36:37], v[36:37], v[224:225]
	v_pk_mul_f32 v[34:35], v[34:35], v[68:69]
	v_pk_mul_f32 v[32:33], v[32:33], v[224:225]
	s_and_saveexec_b64 s[4:5], s[6:7]
	s_cbranch_execz .LBB0_953
	v_pk_fma_f32 v[68:69], v[34:35], v[102:103], v[106:107]
	v_pk_fma_f32 v[70:71], v[32:33], v[100:101], v[104:105]
	v_pk_fma_f32 v[68:69], v[42:43], v[98:99], v[68:69]
	v_pk_fma_f32 v[70:71], v[40:41], v[96:97], v[70:71]
	v_pk_fma_f32 v[56:57], v[82:83], v[56:57], v[68:69]
	v_pk_fma_f32 v[54:55], v[80:81], v[54:55], v[70:71]
	v_pk_fma_f32 v[68:69], v[38:39], v[90:91], v[94:95]
	v_pk_fma_f32 v[70:71], v[36:37], v[88:89], v[92:93]
	v_pk_fma_f32 v[68:69], v[60:61], v[86:87], v[68:69]
	v_pk_fma_f32 v[70:71], v[58:59], v[84:85], v[70:71]
	v_pk_fma_f32 v[46:47], v[78:79], v[46:47], v[68:69]
	v_pk_fma_f32 v[44:45], v[76:77], v[44:45], v[70:71]
	v_mul_f32_e32 v70, 0xbfb8aa3b, v46
	v_mul_f32_e32 v68, 0xbfb8aa3b, v44
	v_mul_f32_e32 v69, 0xbfb8aa3b, v45
	v_mul_f32_e32 v71, 0xbfb8aa3b, v47
	v_exp_f32_e32 v68, v68
	v_exp_f32_e32 v69, v69
	v_exp_f32_e32 v70, v70
	v_exp_f32_e32 v71, v71
	v_add_f32_e32 v68, 1.0, v68
	v_add_f32_e32 v69, 1.0, v69
	v_add_f32_e32 v70, 1.0, v70
	v_add_f32_e32 v71, 1.0, v71
	v_rcp_f32_e32 v68, v68
	v_rcp_f32_e32 v69, v69
	v_rcp_f32_e32 v70, v70
	v_rcp_f32_e32 v71, v71
	v_pk_mul_f32 v[44:45], v[44:45], v[68:69]
	s_nop 0
	v_pk_mul_f32 v[44:45], v[54:55], v[44:45]
	v_pk_mul_f32 v[46:47], v[46:47], v[70:71]
	v_cvt_pk_bf16_f32 v146, v44, v45
	s_nop 0
	v_pk_mul_f32 v[46:47], v[56:57], v[46:47]
	s_nop 0
	v_cvt_pk_bf16_f32 v147, v46, v47
	v_mad_i64_i32 v[46:47], s[6:7], v223, s37, v[50:51]
	global_store_dwordx4 v[46:47], v[144:147], off sc1
.LBB0_953:
	s_or_b64 exec, exec, s[4:5]
	v_mov_b32_e32 v223, v222
	v_mov_b32_e32 v44, v222
	v_mov_b32_e32 v45, v222
	v_pk_mul_f32 v[30:31], v[30:31], v[44:45]
	v_pk_mul_f32 v[28:29], v[28:29], v[222:223]
	v_pk_mul_f32 v[26:27], v[26:27], v[44:45]
	v_pk_mul_f32 v[24:25], v[24:25], v[222:223]
	s_and_saveexec_b64 s[4:5], s[8:9]
	s_cbranch_execz .LBB0_955
	v_pk_fma_f32 v[44:45], v[26:27], v[102:103], v[106:107]
	v_pk_fma_f32 v[46:47], v[24:25], v[100:101], v[104:105]
	v_pk_fma_f32 v[44:45], v[34:35], v[98:99], v[44:45]
	v_pk_fma_f32 v[46:47], v[32:33], v[96:97], v[46:47]
	v_pk_fma_f32 v[42:43], v[42:43], v[82:83], v[44:45]
	v_pk_fma_f32 v[40:41], v[40:41], v[80:81], v[46:47]
	v_pk_fma_f32 v[44:45], v[30:31], v[90:91], v[94:95]
	v_pk_fma_f32 v[46:47], v[28:29], v[88:89], v[92:93]
	v_pk_fma_f32 v[44:45], v[38:39], v[86:87], v[44:45]
	v_pk_fma_f32 v[46:47], v[36:37], v[84:85], v[46:47]
	v_pk_fma_f32 v[44:45], v[60:61], v[78:79], v[44:45]
	v_pk_fma_f32 v[46:47], v[58:59], v[76:77], v[46:47]
	v_mul_f32_e32 v56, 0xbfb8aa3b, v44
	v_mul_f32_e32 v54, 0xbfb8aa3b, v46
	v_mul_f32_e32 v55, 0xbfb8aa3b, v47
	v_mul_f32_e32 v57, 0xbfb8aa3b, v45
	v_exp_f32_e32 v54, v54
	v_exp_f32_e32 v55, v55
	v_exp_f32_e32 v56, v56
	v_exp_f32_e32 v57, v57
	v_add_f32_e32 v54, 1.0, v54
	v_add_f32_e32 v55, 1.0, v55
	v_add_f32_e32 v56, 1.0, v56
	v_add_f32_e32 v57, 1.0, v57
	v_rcp_f32_e32 v54, v54
	v_rcp_f32_e32 v55, v55
	v_rcp_f32_e32 v56, v56
	v_rcp_f32_e32 v57, v57
	v_pk_mul_f32 v[46:47], v[46:47], v[54:55]
	s_nop 0
	v_pk_mul_f32 v[40:41], v[40:41], v[46:47]
	v_pk_mul_f32 v[44:45], v[44:45], v[56:57]
	v_cvt_pk_bf16_f32 v186, v40, v41
	s_nop 0
	v_pk_mul_f32 v[42:43], v[42:43], v[44:45]
	s_nop 0
	v_cvt_pk_bf16_f32 v187, v42, v43
	v_mad_i64_i32 v[42:43], s[6:7], v221, s37, v[50:51]
	global_store_dwordx4 v[42:43], v[184:187], off sc1
; __device__ __forceinline__ unsigned cvt_pk_bf16(float lo, float hi) { unsigned r; asm("v_cvt_pk_bf16_f32 %0, %1, %2" : "=v"(r) : "v"(lo), "v"(hi)); return r; }
;     __device__ __forceinline__ void operator()(const f32x4 (&acc)[2][2][4][2], const CU2& u, int wr, int wc, int fr_, int fq_) const {
;     ...
;             for (int j = 0; j < 8; ++j) {
;                 const f32x4 xg = acc[j >> 2][0][j & 3][n] * rsv[j], xv = acc[j >> 2][1][j & 3][n] * rsv[j];
;                 const f32x4 gc = gb + g2 * xg + g1 * pg1 + g0 * pg2, vc = vb + v2 * xv + v1 * pv1 + v0 * pv2;
;                 f32x4 sg;
; #pragma unroll
;                 for (int e = 0; e < 4; ++e) sg[e] = __builtin_amdgcn_rcpf(1.f + __expf(-gc[e]));
;                 const f32x4 o4 = gc * sg * vc;
;                 pg2 = pg1; pg1 = xg; pv2 = pv1; pv1 = xv;
;                 if (rb + j >= 2 && tb + j < T_) { u32x2 w; w.x = cvt_pk_bf16(o4[0], o4[1]); w.y = cvt_pk_bf16(o4[2], o4[3]); *(u32x2*)(act + (size_t)(tb + j) * FF_ + 128 * u.pn + cl + 4 * n) = w; }
.LBB0_955:
	s_or_b64 exec, exec, s[4:5]
	v_mov_b32_e32 v221, v220
	v_mov_b32_e32 v40, v220
	v_mov_b32_e32 v41, v220
	v_pk_mul_f32 v[22:23], v[22:23], v[40:41]
	v_pk_mul_f32 v[20:21], v[20:21], v[220:221]
	v_pk_mul_f32 v[18:19], v[18:19], v[40:41]
	v_pk_mul_f32 v[16:17], v[16:17], v[220:221]
	s_and_saveexec_b64 s[4:5], s[12:13]
	s_cbranch_execz .LBB0_957
	v_pk_fma_f32 v[40:41], v[18:19], v[102:103], v[106:107]
	v_pk_fma_f32 v[42:43], v[16:17], v[100:101], v[104:105]
	v_pk_fma_f32 v[40:41], v[26:27], v[98:99], v[40:41]
	v_pk_fma_f32 v[42:43], v[24:25], v[96:97], v[42:43]
	v_pk_fma_f32 v[34:35], v[34:35], v[82:83], v[40:41]
	v_pk_fma_f32 v[32:33], v[32:33], v[80:81], v[42:43]
	v_pk_fma_f32 v[40:41], v[22:23], v[90:91], v[94:95]
	v_pk_fma_f32 v[42:43], v[20:21], v[88:89], v[92:93]
	v_pk_fma_f32 v[40:41], v[30:31], v[86:87], v[40:41]
	v_pk_fma_f32 v[42:43], v[28:29], v[84:85], v[42:43]
	v_pk_fma_f32 v[38:39], v[38:39], v[78:79], v[40:41]
	v_pk_fma_f32 v[36:37], v[36:37], v[76:77], v[42:43]
	v_mul_f32_e32 v42, 0xbfb8aa3b, v38
	v_mul_f32_e32 v40, 0xbfb8aa3b, v36
	v_mul_f32_e32 v41, 0xbfb8aa3b, v37
	v_mul_f32_e32 v43, 0xbfb8aa3b, v39
	v_exp_f32_e32 v40, v40
	v_exp_f32_e32 v41, v41
	v_exp_f32_e32 v42, v42
	v_exp_f32_e32 v43, v43
	v_add_f32_e32 v40, 1.0, v40
	v_add_f32_e32 v41, 1.0, v41
	v_add_f32_e32 v42, 1.0, v42
	v_add_f32_e32 v43, 1.0, v43
	v_rcp_f32_e32 v40, v40
	v_rcp_f32_e32 v41, v41
	v_rcp_f32_e32 v42, v42
	v_rcp_f32_e32 v43, v43
	v_pk_mul_f32 v[36:37], v[36:37], v[40:41]
	s_nop 0
	v_pk_mul_f32 v[32:33], v[32:33], v[36:37]
	v_pk_mul_f32 v[38:39], v[38:39], v[42:43]
	v_cvt_pk_bf16_f32 v190, v32, v33
	s_nop 0
	v_pk_mul_f32 v[34:35], v[34:35], v[38:39]
	s_nop 0
	v_cvt_pk_bf16_f32 v191, v34, v35
	v_mad_i64_i32 v[34:35], s[6:7], v219, s37, v[50:51]
	global_store_dwordx4 v[34:35], v[188:191], off sc1
.LBB0_957:
	s_or_b64 exec, exec, s[4:5]
	v_mov_b32_e32 v219, v218
	v_mov_b32_e32 v32, v218
	v_mov_b32_e32 v33, v218
	v_pk_mul_f32 v[14:15], v[14:15], v[32:33]
	v_pk_mul_f32 v[12:13], v[12:13], v[218:219]
	v_pk_mul_f32 v[10:11], v[10:11], v[32:33]
	v_pk_mul_f32 v[8:9], v[8:9], v[218:219]
	s_and_saveexec_b64 s[4:5], s[14:15]
	s_cbranch_execz .LBB0_959
	v_pk_fma_f32 v[32:33], v[10:11], v[102:103], v[106:107]
	v_pk_fma_f32 v[34:35], v[8:9], v[100:101], v[104:105]
	v_pk_fma_f32 v[32:33], v[18:19], v[98:99], v[32:33]
	v_pk_fma_f32 v[34:35], v[16:17], v[96:97], v[34:35]
	v_pk_fma_f32 v[26:27], v[26:27], v[82:83], v[32:33]
	v_pk_fma_f32 v[24:25], v[24:25], v[80:81], v[34:35]
	v_pk_fma_f32 v[32:33], v[14:15], v[90:91], v[94:95]
	v_pk_fma_f32 v[34:35], v[12:13], v[88:89], v[92:93]
	v_pk_fma_f32 v[32:33], v[22:23], v[86:87], v[32:33]
	v_pk_fma_f32 v[34:35], v[20:21], v[84:85], v[34:35]
	v_pk_fma_f32 v[30:31], v[30:31], v[78:79], v[32:33]
	v_pk_fma_f32 v[28:29], v[28:29], v[76:77], v[34:35]
	v_mul_f32_e32 v34, 0xbfb8aa3b, v30
	v_mul_f32_e32 v32, 0xbfb8aa3b, v28
	v_mul_f32_e32 v33, 0xbfb8aa3b, v29
	v_mul_f32_e32 v35, 0xbfb8aa3b, v31
	v_exp_f32_e32 v32, v32
	v_exp_f32_e32 v33, v33
	v_exp_f32_e32 v34, v34
	v_exp_f32_e32 v35, v35
	v_add_f32_e32 v32, 1.0, v32
	v_add_f32_e32 v33, 1.0, v33
	v_add_f32_e32 v34, 1.0, v34
	v_add_f32_e32 v35, 1.0, v35
	v_rcp_f32_e32 v32, v32
	v_rcp_f32_e32 v33, v33
	v_rcp_f32_e32 v34, v34
	v_rcp_f32_e32 v35, v35
	v_pk_mul_f32 v[28:29], v[28:29], v[32:33]
	s_nop 0
	v_pk_mul_f32 v[24:25], v[24:25], v[28:29]
	v_pk_mul_f32 v[30:31], v[30:31], v[34:35]
	v_cvt_pk_bf16_f32 v194, v24, v25
	s_nop 0
	v_pk_mul_f32 v[26:27], v[26:27], v[30:31]
	s_nop 0
	v_cvt_pk_bf16_f32 v195, v26, v27
	v_mad_i64_i32 v[26:27], s[6:7], v217, s37, v[50:51]
	global_store_dwordx4 v[26:27], v[192:195], off sc1
; __device__ __forceinline__ unsigned cvt_pk_bf16(float lo, float hi) { unsigned r; asm("v_cvt_pk_bf16_f32 %0, %1, %2" : "=v"(r) : "v"(lo), "v"(hi)); return r; }
;     __device__ __forceinline__ void operator()(const f32x4 (&acc)[2][2][4][2], const CU2& u, int wr, int wc, int fr_, int fq_) const {
;     ...
;             for (int j = 0; j < 8; ++j) {
;                 const f32x4 xg = acc[j >> 2][0][j & 3][n] * rsv[j], xv = acc[j >> 2][1][j & 3][n] * rsv[j];
;                 const f32x4 gc = gb + g2 * xg + g1 * pg1 + g0 * pg2, vc = vb + v2 * xv + v1 * pv1 + v0 * pv2;
;                 f32x4 sg;
; #pragma unroll
;                 for (int e = 0; e < 4; ++e) sg[e] = __builtin_amdgcn_rcpf(1.f + __expf(-gc[e]));
;                 const f32x4 o4 = gc * sg * vc;
;                 pg2 = pg1; pg1 = xg; pv2 = pv1; pv1 = xv;
;                 if (rb + j >= 2 && tb + j < T_) { u32x2 w; w.x = cvt_pk_bf16(o4[0], o4[1]); w.y = cvt_pk_bf16(o4[2], o4[3]); *(u32x2*)(act + (size_t)(tb + j) * FF_ + 128 * u.pn + cl + 4 * n) = w; }
.LBB0_959:
	s_or_b64 exec, exec, s[4:5]
	v_mov_b32_e32 v217, v216
	v_mov_b32_e32 v24, v216
	v_mov_b32_e32 v25, v216
	v_pk_mul_f32 v[6:7], v[6:7], v[24:25]
	v_pk_mul_f32 v[4:5], v[4:5], v[216:217]
	v_pk_mul_f32 v[2:3], v[2:3], v[24:25]
	v_pk_mul_f32 v[0:1], v[0:1], v[216:217]
	s_and_saveexec_b64 s[4:5], s[26:27]
	s_cbranch_execz .LBB0_961
	v_pk_fma_f32 v[24:25], v[2:3], v[102:103], v[106:107]
	v_pk_fma_f32 v[26:27], v[0:1], v[100:101], v[104:105]
	v_pk_fma_f32 v[24:25], v[10:11], v[98:99], v[24:25]
	v_pk_fma_f32 v[26:27], v[8:9], v[96:97], v[26:27]
	v_pk_fma_f32 v[18:19], v[18:19], v[82:83], v[24:25]
	v_pk_fma_f32 v[16:17], v[16:17], v[80:81], v[26:27]
	v_pk_fma_f32 v[24:25], v[6:7], v[90:91], v[94:95]
	v_pk_fma_f32 v[26:27], v[4:5], v[88:89], v[92:93]
	v_pk_fma_f32 v[24:25], v[14:15], v[86:87], v[24:25]
	v_pk_fma_f32 v[26:27], v[12:13], v[84:85], v[26:27]
	v_pk_fma_f32 v[22:23], v[22:23], v[78:79], v[24:25]
	v_pk_fma_f32 v[20:21], v[20:21], v[76:77], v[26:27]
	v_mul_f32_e32 v26, 0xbfb8aa3b, v22
	v_mul_f32_e32 v24, 0xbfb8aa3b, v20
	v_mul_f32_e32 v25, 0xbfb8aa3b, v21
	v_mul_f32_e32 v27, 0xbfb8aa3b, v23
	v_exp_f32_e32 v24, v24
	v_exp_f32_e32 v25, v25
	v_exp_f32_e32 v26, v26
	v_exp_f32_e32 v27, v27
	v_add_f32_e32 v24, 1.0, v24
	v_add_f32_e32 v25, 1.0, v25
	v_add_f32_e32 v26, 1.0, v26
	v_add_f32_e32 v27, 1.0, v27
	v_rcp_f32_e32 v24, v24
	v_rcp_f32_e32 v25, v25
	v_rcp_f32_e32 v26, v26
	v_rcp_f32_e32 v27, v27
	v_pk_mul_f32 v[20:21], v[20:21], v[24:25]
	s_nop 0
	v_pk_mul_f32 v[16:17], v[16:17], v[20:21]
	v_pk_mul_f32 v[22:23], v[22:23], v[26:27]
	v_cvt_pk_bf16_f32 v198, v16, v17
	s_nop 0
	v_pk_mul_f32 v[18:19], v[18:19], v[22:23]
	s_nop 0
	v_cvt_pk_bf16_f32 v199, v18, v19
	v_mad_i64_i32 v[18:19], s[6:7], v246, s37, v[50:51]
	global_store_dwordx4 v[18:19], v[196:199], off sc1
.LBB0_961:
	s_or_b64 exec, exec, s[4:5]
	s_and_saveexec_b64 s[4:5], s[28:29]
	s_cbranch_execz .LBB0_963
	v_pk_fma_f32 v[16:17], v[110:111], v[102:103], v[106:107]
	v_pk_fma_f32 v[18:19], v[62:63], v[100:101], v[104:105]
	v_pk_fma_f32 v[16:17], v[2:3], v[98:99], v[16:17]
	v_pk_fma_f32 v[18:19], v[0:1], v[96:97], v[18:19]
	v_pk_fma_f32 v[10:11], v[10:11], v[82:83], v[16:17]
	v_pk_fma_f32 v[8:9], v[8:9], v[80:81], v[18:19]
	v_pk_fma_f32 v[16:17], v[64:65], v[90:91], v[94:95]
	v_pk_fma_f32 v[18:19], v[48:49], v[88:89], v[92:93]
	v_pk_fma_f32 v[16:17], v[6:7], v[86:87], v[16:17]
	v_pk_fma_f32 v[18:19], v[4:5], v[84:85], v[18:19]
	v_pk_fma_f32 v[14:15], v[14:15], v[78:79], v[16:17]
	v_pk_fma_f32 v[12:13], v[12:13], v[76:77], v[18:19]
	v_mul_f32_e32 v18, 0xbfb8aa3b, v14
	v_mul_f32_e32 v16, 0xbfb8aa3b, v12
	v_mul_f32_e32 v17, 0xbfb8aa3b, v13
	v_mul_f32_e32 v19, 0xbfb8aa3b, v15
	v_exp_f32_e32 v16, v16
	v_exp_f32_e32 v17, v17
	v_exp_f32_e32 v18, v18
	v_exp_f32_e32 v19, v19
	v_add_f32_e32 v16, 1.0, v16
	v_add_f32_e32 v17, 1.0, v17
	v_add_f32_e32 v18, 1.0, v18
	v_add_f32_e32 v19, 1.0, v19
	v_rcp_f32_e32 v16, v16
	v_rcp_f32_e32 v17, v17
	v_rcp_f32_e32 v18, v18
	v_rcp_f32_e32 v19, v19
	v_pk_mul_f32 v[12:13], v[12:13], v[16:17]
	s_nop 0
	v_pk_mul_f32 v[8:9], v[8:9], v[12:13]
	v_pk_mul_f32 v[14:15], v[14:15], v[18:19]
	v_cvt_pk_bf16_f32 v250, v8, v9
	s_nop 0
	v_pk_mul_f32 v[10:11], v[10:11], v[14:15]
	s_nop 0
	v_cvt_pk_bf16_f32 v251, v10, v11
	v_mad_i64_i32 v[10:11], s[6:7], v245, s37, v[50:51]
	global_store_dwordx4 v[10:11], v[248:251], off sc1
.LBB0_963:
	s_or_b64 exec, exec, s[4:5]
	s_and_saveexec_b64 s[4:5], s[0:1]
	s_cbranch_execz .LBB0_965
	v_pk_fma_f32 v[12:13], v[52:53], v[88:89], v[92:93]
	v_pk_fma_f32 v[8:9], v[112:113], v[102:103], v[106:107]
	v_pk_fma_f32 v[12:13], v[48:49], v[84:85], v[12:13]
	v_pk_fma_f32 v[10:11], v[66:67], v[100:101], v[104:105]
	v_pk_fma_f32 v[4:5], v[4:5], v[76:77], v[12:13]
	v_pk_fma_f32 v[8:9], v[110:111], v[98:99], v[8:9]
	v_mul_f32_e32 v12, 0xbfb8aa3b, v4
	v_exp_f32_e32 v14, v12
	v_pk_fma_f32 v[12:13], v[108:109], v[90:91], v[94:95]
	v_pk_fma_f32 v[10:11], v[62:63], v[96:97], v[10:11]
	v_pk_fma_f32 v[12:13], v[64:65], v[86:87], v[12:13]
	v_pk_fma_f32 v[2:3], v[2:3], v[82:83], v[8:9]
	v_pk_fma_f32 v[6:7], v[6:7], v[78:79], v[12:13]
	v_add_f32_e32 v12, 1.0, v14
	v_mul_f32_e32 v13, 0xbfb8aa3b, v5
	v_mul_f32_e32 v14, 0xbfb8aa3b, v6
	v_mul_f32_e32 v15, 0xbfb8aa3b, v7
	v_exp_f32_e32 v13, v13
	v_exp_f32_e32 v14, v14
	v_exp_f32_e32 v15, v15
	v_rcp_f32_e32 v12, v12
	v_add_f32_e32 v13, 1.0, v13
	v_add_f32_e32 v14, 1.0, v14
	v_add_f32_e32 v15, 1.0, v15
	v_rcp_f32_e32 v14, v14
	v_rcp_f32_e32 v15, v15
	v_rcp_f32_e32 v13, v13
	v_pk_fma_f32 v[0:1], v[0:1], v[80:81], v[10:11]
	v_pk_mul_f32 v[6:7], v[6:7], v[14:15]
	v_pk_mul_f32 v[4:5], v[4:5], v[12:13]
	v_pk_mul_f32 v[2:3], v[2:3], v[6:7]
	v_pk_mul_f32 v[0:1], v[0:1], v[4:5]
	s_nop 0
	v_cvt_pk_bf16_f32 v122, v0, v1
	v_cvt_pk_bf16_f32 v123, v2, v3
	v_mad_i64_i32 v[2:3], s[0:1], v244, s37, v[50:51]
	global_store_dwordx4 v[2:3], v[120:123], off sc1
